# rwkv light prep: second item's LDS reads also issued at the chunk-loop top (scan-temporary registers)
# baseline (speedup 1.0000x reference)
; template <bool DUAL>
; __device__ __forceinline__ void rwkv_tile(const Params& p, int l, int tile, unsigned char* smem) {
;     ...
;       const int i = (tid >> 4) + 16 * k;
;       const int ri = (d == 0) ? i + 1 : 32 - i;
;       const bf16_t* r0 = raw + ri * 192 + lc;
;       const bf16_t* q0 = pre + (ri - 1) * 192 + lc;
;       float rs[4], ksv[4], vs[4];
; #pragma unroll
;       for (int sl = 0; sl < 3; ++sl) {
;         const uint2 uc = *(const uint2*)(r0 + sl * 64), up = *(const uint2*)(r0 + sl * 64 - 192), un = *(const uint2*)(r0 + sl * 64 + 192);
.LBB0_1411:
	ds_read2_b64 v[60:63], v107 offset1:16
	ds_read_b64 v[72:73], v108
	ds_read2_b64 v[64:67], v107 offset0:32 offset1:48
	ds_read_b64 v[76:77], v109
	ds_read_b64 v[78:79], v110
	ds_read_b64 v[122:123], v111 offset:12928
	ds_read2_b64 v[68:71], v107 offset0:64 offset1:80
	ds_read2_b64 v[216:219], v112 offset1:16
	ds_read_b64 v[156:157], v113
	ds_read2_b64 v[220:223], v112 offset0:32 offset1:48
	ds_read_b64 v[160:161], v114
	ds_read_b64 v[162:163], v115
	ds_read_b64 v[228:229], v116 offset:12928
	ds_read2_b64 v[224:227], v112 offset0:64 offset1:80
	s_add_i32 s52, s28, 1
	s_cmpk_eq_i32 s28, 0x87
	s_cbranch_scc1 .Lrw_du_nopf
	s_lshl_b32 s53, s52, 5
	s_sub_i32 s54, 0x11e0, s53
	s_and_b64 s[50:51], s[36:37], exec
	s_cselect_b32 s53, s53, s54
	s_add_i32 s54, s53, -1
	s_cmpk_eq_u32 s52, 0x87
	s_cbranch_scc1 .Lrw_du_pfslow
	s_and_saveexec_b64 s[50:51], s[42:43]
	v_add_u32_e32 v32, s54, v97
	v_lshlrev_b32_e32 v32, 11, v32
	v_mov_b32_e32 v33, v164
	v_lshl_add_u64 v[32:33], v[80:81], 0, v[32:33]
	global_load_dwordx4 v[32:35], v[32:33], off
	v_add_u32_e32 v28, s54, v98
	v_lshlrev_b32_e32 v28, 11, v28
	v_mov_b32_e32 v29, v164
	v_lshl_add_u64 v[28:29], v[80:81], 0, v[28:29]
	global_load_dwordx4 v[28:31], v[28:29], off
	v_add_u32_e32 v36, s54, v99
	v_lshlrev_b32_e32 v36, 11, v36
	v_mov_b32_e32 v37, v164
	v_lshl_add_u64 v[36:37], v[80:81], 0, v[36:37]
	global_load_dwordx4 v[36:39], v[36:37], off
	v_add_u32_e32 v44, s53, v97
	v_mov_b32_e32 v45, v164
	v_lshlrev_b64 v[44:45], 10, v[44:45]
	v_lshl_add_u64 v[44:45], v[82:83], 0, v[44:45]
	global_load_dwordx4 v[44:47], v[44:45], off
	v_add_u32_e32 v48, s53, v98
	v_mov_b32_e32 v49, v164
	v_lshlrev_b64 v[48:49], 10, v[48:49]
	v_lshl_add_u64 v[48:49], v[82:83], 0, v[48:49]
	global_load_dwordx4 v[48:51], v[48:49], off
	v_add_u32_e32 v52, s53, v99
	v_mov_b32_e32 v53, v164
	v_lshlrev_b64 v[52:53], 10, v[52:53]
	v_lshl_add_u64 v[52:53], v[82:83], 0, v[52:53]
	global_load_dwordx4 v[52:55], v[52:53], off
	s_mov_b64 exec, s[50:51]
	s_and_b64 exec, exec, s[44:45]
	v_add_u32_e32 v40, s54, v100
	v_lshlrev_b32_e32 v40, 11, v40
	v_mov_b32_e32 v41, v164
	v_lshl_add_u64 v[40:41], v[80:81], 0, v[40:41]
	global_load_dwordx4 v[40:43], v[40:41], off
	s_mov_b64 exec, s[50:51]
	s_and_b64 exec, exec, s[46:47]
	v_add_u32_e32 v56, s53, v100
	v_mov_b32_e32 v57, v164
	v_lshlrev_b64 v[56:57], 10, v[56:57]
	v_lshl_add_u64 v[56:57], v[82:83], 0, v[56:57]
	global_load_dwordx4 v[56:59], v[56:57], off
	s_mov_b64 exec, s[50:51]
	s_branch .Lrw_du_nopf

; template <bool DUAL>
; __device__ __forceinline__ void rwkv_tile(const Params& p, int l, int tile, unsigned char* smem) {
;     ...
;       float rs[4], ksv[4], vs[4];
; #pragma unroll
;       for (int sl = 0; sl < 3; ++sl) {
;         const uint2 uc = *(const uint2*)(r0 + sl * 64), up = *(const uint2*)(r0 + sl * 64 - 192), un = *(const uint2*)(r0 + sl * 64 + 192);
;         const float4 m0 = (sl == 0) ? m0r : ((sl == 1) ? m0k : m0v);
;         const float4 m1 = (sl == 0) ? m1r : ((sl == 1) ? m1k : m1v);
;         float* dst = (sl == 0) ? rs : ((sl == 1) ? ksv : vs);
;         float u, a, n;
;         u = __uint_as_float(uc.x << 16); a = __uint_as_float(up.x << 16); n = __uint_as_float(un.x << 16);
;         dst[0] = u + m0.x * (a - u) + m1.x * (n - u);
;         u = __uint_as_float(uc.x & 0xffff0000u); a = __uint_as_float(up.x & 0xffff0000u); n = __uint_as_float(un.x & 0xffff0000u);
;         dst[1] = u + m0.y * (a - u) + m1.y * (n - u);
;         u = __uint_as_float(uc.y << 16); a = __uint_as_float(up.y << 16); n = __uint_as_float(un.y << 16);
;         dst[2] = u + m0.z * (a - u) + m1.z * (n - u);
;         u = __uint_as_float(uc.y & 0xffff0000u); a = __uint_as_float(up.y & 0xffff0000u); n = __uint_as_float(un.y & 0xffff0000u);
;         dst[3] = u + m0.w * (a - u) + m1.w * (n - u);
;       }
;       const uint2 ue = *(const uint2*)(q0), ua = *(const uint2*)(q0 + 64), uk = *(const uint2*)(q0 + 128);
;       const float ew[4] = {__uint_as_float(ue.x << 16), __uint_as_float(ue.x & 0xffff0000u), __uint_as_float(ue.y << 16), __uint_as_float(ue.y & 0xffff0000u)};
;       const float av[4] = {__uint_as_float(ua.x << 16), __uint_as_float(ua.x & 0xffff0000u), __uint_as_float(ua.y << 16), __uint_as_float(ua.y & 0xffff0000u)};
;       const float kk[4] = {__uint_as_float(uk.x << 16), __uint_as_float(uk.x & 0xffff0000u), __uint_as_float(uk.y << 16), __uint_as_float(uk.y & 0xffff0000u)};
;       const float kav[4] = {ka4.x, ka4.y, ka4.z, ka4.w};
;       float4 o0, o1, o2, o3, o4, o5;
;       float* f0 = (float*)&o0; float* f1 = (float*)&o1; float* f2 = (float*)&o2; float* f3 = (float*)&o3; float* f4 = (float*)&o4; float* f5 = (float*)&o5;
; #pragma unroll
;       for (int e = 0; e < 4; ++e) {
;         f0[e] = __expf(-ew[e]);
;         f1[e] = kk[e];
;         f2[e] = kk[e] * av[e];
;         f3[e] = ksv[e] * (1.f + (av[e] - 1.f) * kav[e]);
;         f4[e] = rs[e];
.Lrw_du_nopf:
	s_waitcnt lgkmcnt(13)
	v_lshlrev_b32_e32 v74, 16, v60
	v_and_b32_e32 v75, 0xffff0000, v60
	v_add_u32_e32 v60, 0x3000, v111
	v_lshlrev_b32_e32 v128, 16, v61
	v_and_b32_e32 v129, 0xffff0000, v61
	v_lshlrev_b32_e32 v132, 16, v62
	v_and_b32_e32 v133, 0xffff0000, v62
	v_lshlrev_b32_e32 v138, 16, v63
	v_and_b32_e32 v139, 0xffff0000, v63
	ds_read2_b64 v[60:63], v60 offset0:48 offset1:64
	s_waitcnt lgkmcnt(12)
	v_lshlrev_b32_e32 v142, 16, v64
	v_and_b32_e32 v143, 0xffff0000, v64
	s_waitcnt lgkmcnt(8)
	v_lshlrev_b32_e32 v136, 16, v68
	v_and_b32_e32 v137, 0xffff0000, v68
	s_waitcnt lgkmcnt(0)
	v_lshlrev_b32_e32 v64, 16, v60
	v_and_b32_e32 v60, 0xffff0000, v60
	v_lshlrev_b32_e32 v68, 16, v61
	v_mul_f32_e32 v60, 0xbfb8aa3b, v60
	v_lshlrev_b32_e32 v130, 16, v67
	v_and_b32_e32 v131, 0xffff0000, v67
	v_and_b32_e32 v61, 0xffff0000, v61
	v_exp_f32_e32 v67, v60
	v_mul_f32_e32 v60, 0xbfb8aa3b, v68
	v_mul_f32_e32 v64, 0xbfb8aa3b, v64
	v_exp_f32_e32 v68, v60
	v_mul_f32_e32 v60, 0xbfb8aa3b, v61
	v_lshlrev_b32_e32 v126, 16, v66
	v_and_b32_e32 v127, 0xffff0000, v66
	v_lshlrev_b32_e32 v140, 16, v69
	v_and_b32_e32 v141, 0xffff0000, v69
	v_exp_f32_e32 v66, v64
	v_exp_f32_e32 v69, v60
	v_lshlrev_b32_e32 v121, 16, v62
	v_lshlrev_b32_e32 v150, 16, v123
	v_lshlrev_b32_e32 v153, 16, v63
	ds_write_b128 v119, v[66:69] offset:25344
	v_and_b32_e32 v67, 16, v62
	v_and_b32_e32 v66, 0xffff0000, v122
	v_lshlrev_b32_e32 v68, 16, v122
	v_and_b32_e32 v69, 0xffff0000, v62
	v_pk_mov_b32 v[60:61], v[120:121], v[66:67] op_sel:[1,0]
	v_and_b32_e32 v155, 16, v63
	v_and_b32_e32 v154, 0xffff0000, v123
	v_lshlrev_b32_e32 v134, 16, v76
	v_and_b32_e32 v135, 0xffff0000, v76
	v_lshlrev_b32_e32 v148, 16, v65
	v_and_b32_e32 v149, 0xffff0000, v65
	v_pk_mul_f32 v[60:61], v[68:69], v[60:61]
	v_and_b32_e32 v151, 0xffff0000, v63
	v_pk_mov_b32 v[62:63], v[152:153], v[154:155] op_sel:[1,0]
	v_mov_b32_e32 v64, v68
	v_mov_b32_e32 v65, v66
	v_mov_b32_e32 v66, v150
	v_mov_b32_e32 v67, v154
	v_pk_mul_f32 v[62:63], v[150:151], v[62:63]
	ds_write_b128 v119, v[64:67] offset:25600
	ds_write_b128 v119, v[60:63] offset:25856
	v_pk_add_f32 v[60:61], v[134:135], v[132:133] neg_lo:[0,1] neg_hi:[0,1]
	v_pk_add_f32 v[62:63], v[136:137], v[132:133] neg_lo:[0,1] neg_hi:[0,1]

; template <bool DUAL>
; __device__ __forceinline__ void rwkv_tile(const Params& p, int l, int tile, unsigned char* smem) {
;     ...
;         u = __uint_as_float(uc.x << 16); a = __uint_as_float(up.x << 16); n = __uint_as_float(un.x << 16);
;         dst[0] = u + m0.x * (a - u) + m1.x * (n - u);
;         u = __uint_as_float(uc.x & 0xffff0000u); a = __uint_as_float(up.x & 0xffff0000u); n = __uint_as_float(un.x & 0xffff0000u);
;         dst[1] = u + m0.y * (a - u) + m1.y * (n - u);
;         u = __uint_as_float(uc.y << 16); a = __uint_as_float(up.y << 16); n = __uint_as_float(un.y << 16);
;         dst[2] = u + m0.z * (a - u) + m1.z * (n - u);
;         u = __uint_as_float(uc.y & 0xffff0000u); a = __uint_as_float(up.y & 0xffff0000u); n = __uint_as_float(un.y & 0xffff0000u);
;         dst[3] = u + m0.w * (a - u) + m1.w * (n - u);
	v_pk_fma_f32 v[60:61], v[12:13], v[60:61], v[132:133]
	v_mov_b32_e32 v68, v121

; template <bool DUAL>
; __device__ __forceinline__ void rwkv_tile(const Params& p, int l, int tile, unsigned char* smem) {
;     ...
;         u = __uint_as_float(uc.x << 16); a = __uint_as_float(up.x << 16); n = __uint_as_float(un.x << 16);
;         dst[0] = u + m0.x * (a - u) + m1.x * (n - u);
;         u = __uint_as_float(uc.x & 0xffff0000u); a = __uint_as_float(up.x & 0xffff0000u); n = __uint_as_float(un.x & 0xffff0000u);
;         dst[1] = u + m0.y * (a - u) + m1.y * (n - u);
;         u = __uint_as_float(uc.y << 16); a = __uint_as_float(up.y << 16); n = __uint_as_float(un.y << 16);
;         dst[2] = u + m0.z * (a - u) + m1.z * (n - u);
;         u = __uint_as_float(uc.y & 0xffff0000u); a = __uint_as_float(up.y & 0xffff0000u); n = __uint_as_float(un.y & 0xffff0000u);
;         dst[3] = u + m0.w * (a - u) + m1.w * (n - u);
;       }
;       const uint2 ue = *(const uint2*)(q0), ua = *(const uint2*)(q0 + 64), uk = *(const uint2*)(q0 + 128);
;       const float ew[4] = {__uint_as_float(ue.x << 16), __uint_as_float(ue.x & 0xffff0000u), __uint_as_float(ue.y << 16), __uint_as_float(ue.y & 0xffff0000u)};
;       const float av[4] = {__uint_as_float(ua.x << 16), __uint_as_float(ua.x & 0xffff0000u), __uint_as_float(ua.y << 16), __uint_as_float(ua.y & 0xffff0000u)};
;       const float kk[4] = {__uint_as_float(uk.x << 16), __uint_as_float(uk.x & 0xffff0000u), __uint_as_float(uk.y << 16), __uint_as_float(uk.y & 0xffff0000u)};
;       const float kav[4] = {ka4.x, ka4.y, ka4.z, ka4.w};
;       float4 o0, o1, o2, o3, o4, o5;
;       float* f0 = (float*)&o0; float* f1 = (float*)&o1; float* f2 = (float*)&o2; float* f3 = (float*)&o3; float* f4 = (float*)&o4; float* f5 = (float*)&o5;
; #pragma unroll
;       for (int e = 0; e < 4; ++e) {
;         f0[e] = __expf(-ew[e]);
;         f1[e] = kk[e];
;         f2[e] = kk[e] * av[e];
;         f3[e] = ksv[e] * (1.f + (av[e] - 1.f) * kav[e]);
	v_pk_fma_f32 v[60:61], v[20:21], v[62:63], v[60:61]
	v_pk_add_f32 v[62:63], v[68:69], -1.0 op_sel_hi:[1,0]
	v_lshlrev_b32_e32 v76, 16, v77
	v_and_b32_e32 v77, 0xffff0000, v77

; template <bool DUAL>
; __device__ __forceinline__ void rwkv_tile(const Params& p, int l, int tile, unsigned char* smem) {
;     ...
;       const int i = (tid >> 4) + 16 * k;
;       const int ri = (d == 0) ? i + 1 : 32 - i;
;       const bf16_t* r0 = raw + ri * 192 + lc;
;       const bf16_t* q0 = pre + (ri - 1) * 192 + lc;
;       float rs[4], ksv[4], vs[4];
; #pragma unroll
;       for (int sl = 0; sl < 3; ++sl) {
;         const uint2 uc = *(const uint2*)(r0 + sl * 64), up = *(const uint2*)(r0 + sl * 64 - 192), un = *(const uint2*)(r0 + sl * 64 + 192);
;         const float4 m0 = (sl == 0) ? m0r : ((sl == 1) ? m0k : m0v);
;         const float4 m1 = (sl == 0) ? m1r : ((sl == 1) ? m1k : m1v);
;         float* dst = (sl == 0) ? rs : ((sl == 1) ? ksv : vs);
;         float u, a, n;
;         u = __uint_as_float(uc.x << 16); a = __uint_as_float(up.x << 16); n = __uint_as_float(un.x << 16);
;         dst[0] = u + m0.x * (a - u) + m1.x * (n - u);
;         u = __uint_as_float(uc.x & 0xffff0000u); a = __uint_as_float(up.x & 0xffff0000u); n = __uint_as_float(un.x & 0xffff0000u);
;         dst[1] = u + m0.y * (a - u) + m1.y * (n - u);
;         u = __uint_as_float(uc.y << 16); a = __uint_as_float(up.y << 16); n = __uint_as_float(un.y << 16);
;         dst[2] = u + m0.z * (a - u) + m1.z * (n - u);
;         u = __uint_as_float(uc.y & 0xffff0000u); a = __uint_as_float(up.y & 0xffff0000u); n = __uint_as_float(un.y & 0xffff0000u);
;         dst[3] = u + m0.w * (a - u) + m1.w * (n - u);
;       }
;       const uint2 ue = *(const uint2*)(q0), ua = *(const uint2*)(q0 + 64), uk = *(const uint2*)(q0 + 128);
;       const float ew[4] = {__uint_as_float(ue.x << 16), __uint_as_float(ue.x & 0xffff0000u), __uint_as_float(ue.y << 16), __uint_as_float(ue.y & 0xffff0000u)};
;       const float av[4] = {__uint_as_float(ua.x << 16), __uint_as_float(ua.x & 0xffff0000u), __uint_as_float(ua.y << 16), __uint_as_float(ua.y & 0xffff0000u)};
;       const float kk[4] = {__uint_as_float(uk.x << 16), __uint_as_float(uk.x & 0xffff0000u), __uint_as_float(uk.y << 16), __uint_as_float(uk.y & 0xffff0000u)};
;       const float kav[4] = {ka4.x, ka4.y, ka4.z, ka4.w};
;       float4 o0, o1, o2, o3, o4, o5;
;       float* f0 = (float*)&o0; float* f1 = (float*)&o1; float* f2 = (float*)&o2; float* f3 = (float*)&o3; float* f4 = (float*)&o4; float* f5 = (float*)&o5;
; #pragma unroll
	v_pk_fma_f32 v[62:63], v[24:25], v[62:63], 1.0 op_sel_hi:[1,1,0]
	v_pk_add_f32 v[64:65], v[140:141], v[138:139] neg_lo:[0,1] neg_hi:[0,1]
	v_pk_mul_f32 v[60:61], v[60:61], v[62:63]
	v_pk_add_f32 v[62:63], v[76:77], v[138:139] neg_lo:[0,1] neg_hi:[0,1]
	v_mov_b32_e32 v150, v153
	v_pk_fma_f32 v[62:63], v[14:15], v[62:63], v[138:139]
	v_lshlrev_b32_e32 v124, 16, v72
	v_pk_fma_f32 v[62:63], v[22:23], v[64:65], v[62:63]
	v_pk_add_f32 v[64:65], v[150:151], -1.0 op_sel_hi:[1,0]
	v_and_b32_e32 v125, 0xffff0000, v72
	v_pk_fma_f32 v[64:65], v[26:27], v[64:65], 1.0 op_sel_hi:[1,1,0]
	v_lshlrev_b32_e32 v72, 16, v73
	v_pk_mul_f32 v[62:63], v[62:63], v[64:65]
	ds_write_b128 v119, v[60:63] offset:26112
	v_pk_add_f32 v[60:61], v[124:125], v[74:75] neg_lo:[0,1] neg_hi:[0,1]
	v_and_b32_e32 v73, 0xffff0000, v73
	v_pk_fma_f32 v[60:61], v[8:9], v[60:61], v[74:75]
	v_pk_add_f32 v[62:63], v[126:127], v[74:75] neg_lo:[0,1] neg_hi:[0,1]
	v_pk_add_f32 v[64:65], v[130:131], v[128:129] neg_lo:[0,1] neg_hi:[0,1]
	v_pk_fma_f32 v[60:61], v[0:1], v[62:63], v[60:61]
	v_pk_add_f32 v[62:63], v[72:73], v[128:129] neg_lo:[0,1] neg_hi:[0,1]
	v_lshlrev_b32_e32 v144, 16, v78
	v_pk_fma_f32 v[62:63], v[10:11], v[62:63], v[128:129]
	v_and_b32_e32 v145, 0xffff0000, v78
	v_pk_fma_f32 v[62:63], v[2:3], v[64:65], v[62:63]
	v_lshlrev_b32_e32 v146, 16, v70
	v_and_b32_e32 v147, 0xffff0000, v70
	ds_write_b128 v119, v[60:63] offset:26368
	v_pk_add_f32 v[60:61], v[144:145], v[142:143] neg_lo:[0,1] neg_hi:[0,1]
	v_lshlrev_b32_e32 v78, 16, v79
	v_and_b32_e32 v79, 0xffff0000, v79
	v_pk_fma_f32 v[60:61], v[4:5], v[60:61], v[142:143]
	v_pk_add_f32 v[62:63], v[146:147], v[142:143] neg_lo:[0,1] neg_hi:[0,1]
	v_lshlrev_b32_e32 v70, 16, v71
	v_and_b32_e32 v71, 0xffff0000, v71
	v_pk_fma_f32 v[60:61], v[16:17], v[62:63], v[60:61]
	v_pk_add_f32 v[62:63], v[78:79], v[148:149] neg_lo:[0,1] neg_hi:[0,1]
	v_pk_add_f32 v[64:65], v[70:71], v[148:149] neg_lo:[0,1] neg_hi:[0,1]
	v_pk_fma_f32 v[62:63], v[6:7], v[62:63], v[148:149]
	s_add_i32 s52, s28, 1
	v_pk_fma_f32 v[62:63], v[18:19], v[64:65], v[62:63]
	ds_write_b128 v119, v[60:63] offset:26624
	s_waitcnt lgkmcnt(6)
	v_lshlrev_b32_e32 v158, 16, v216
	v_and_b32_e32 v159, 0xffff0000, v216
	v_add_u32_e32 v216, 0x3000, v116
	v_lshlrev_b32_e32 v128, 16, v217
	v_and_b32_e32 v129, 0xffff0000, v217
	v_lshlrev_b32_e32 v132, 16, v218
	v_and_b32_e32 v133, 0xffff0000, v218
	v_lshlrev_b32_e32 v138, 16, v219
	v_and_b32_e32 v139, 0xffff0000, v219
	ds_read2_b64 v[216:219], v216 offset0:48 offset1:64
	s_waitcnt lgkmcnt(5)
	v_lshlrev_b32_e32 v142, 16, v220
	v_and_b32_e32 v143, 0xffff0000, v220
	s_waitcnt lgkmcnt(1)
	v_lshlrev_b32_e32 v136, 16, v224
	v_and_b32_e32 v137, 0xffff0000, v224
	s_waitcnt lgkmcnt(0)
	v_lshlrev_b32_e32 v220, 16, v216
	v_and_b32_e32 v216, 0xffff0000, v216
	v_lshlrev_b32_e32 v224, 16, v217
	v_mul_f32_e32 v216, 0xbfb8aa3b, v216
	v_lshlrev_b32_e32 v130, 16, v223
	v_and_b32_e32 v131, 0xffff0000, v223
	v_and_b32_e32 v217, 0xffff0000, v217
	v_exp_f32_e32 v223, v216
	v_mul_f32_e32 v216, 0xbfb8aa3b, v224
	v_mul_f32_e32 v220, 0xbfb8aa3b, v220
	v_exp_f32_e32 v224, v216
	v_mul_f32_e32 v216, 0xbfb8aa3b, v217
	v_lshlrev_b32_e32 v126, 16, v222
	v_and_b32_e32 v127, 0xffff0000, v222
	v_lshlrev_b32_e32 v140, 16, v225
	v_and_b32_e32 v141, 0xffff0000, v225
	v_exp_f32_e32 v222, v220
	v_exp_f32_e32 v225, v216
	v_lshlrev_b32_e32 v121, 16, v218
	v_lshlrev_b32_e32 v150, 16, v229
	v_lshlrev_b32_e32 v153, 16, v219
	ds_write_b128 v119, v[222:225] offset:49920
	v_and_b32_e32 v223, 16, v218
	v_and_b32_e32 v222, 0xffff0000, v228
	v_lshlrev_b32_e32 v224, 16, v228
	v_and_b32_e32 v225, 0xffff0000, v218
	v_pk_mov_b32 v[216:217], v[120:121], v[222:223] op_sel:[1,0]
	v_and_b32_e32 v155, 16, v219
	v_and_b32_e32 v154, 0xffff0000, v229
	v_lshlrev_b32_e32 v134, 16, v160
	v_and_b32_e32 v135, 0xffff0000, v160
	v_lshlrev_b32_e32 v148, 16, v221
	v_and_b32_e32 v149, 0xffff0000, v221
	v_pk_mul_f32 v[216:217], v[224:225], v[216:217]
	v_and_b32_e32 v151, 0xffff0000, v219
	v_pk_mov_b32 v[218:219], v[152:153], v[154:155] op_sel:[1,0]
	v_mov_b32_e32 v220, v224
	v_mov_b32_e32 v221, v222
	v_mov_b32_e32 v222, v150
	v_mov_b32_e32 v223, v154
	v_pk_mul_f32 v[218:219], v[150:151], v[218:219]
	ds_write_b128 v119, v[220:223] offset:50176
	ds_write_b128 v119, v[216:219] offset:50432
	v_pk_add_f32 v[216:217], v[134:135], v[132:133] neg_lo:[0,1] neg_hi:[0,1]
	v_pk_add_f32 v[218:219], v[136:137], v[132:133] neg_lo:[0,1] neg_hi:[0,1]
	v_pk_fma_f32 v[216:217], v[12:13], v[216:217], v[132:133]
	v_mov_b32_e32 v224, v121
	v_pk_fma_f32 v[216:217], v[20:21], v[218:219], v[216:217]
	v_pk_add_f32 v[218:219], v[224:225], -1.0 op_sel_hi:[1,0]
	v_lshlrev_b32_e32 v160, 16, v161
	v_and_b32_e32 v161, 0xffff0000, v161
	v_pk_fma_f32 v[218:219], v[24:25], v[218:219], 1.0 op_sel_hi:[1,1,0]
	v_pk_add_f32 v[220:221], v[140:141], v[138:139] neg_lo:[0,1] neg_hi:[0,1]
	v_pk_mul_f32 v[216:217], v[216:217], v[218:219]
	v_pk_add_f32 v[218:219], v[160:161], v[138:139] neg_lo:[0,1] neg_hi:[0,1]
	v_mov_b32_e32 v150, v153
	v_pk_fma_f32 v[218:219], v[14:15], v[218:219], v[138:139]
	v_lshlrev_b32_e32 v124, 16, v156
	v_pk_fma_f32 v[218:219], v[22:23], v[220:221], v[218:219]
	v_pk_add_f32 v[220:221], v[150:151], -1.0 op_sel_hi:[1,0]
	v_and_b32_e32 v125, 0xffff0000, v156
	v_pk_fma_f32 v[220:221], v[26:27], v[220:221], 1.0 op_sel_hi:[1,1,0]
	v_lshlrev_b32_e32 v156, 16, v157
	v_pk_mul_f32 v[218:219], v[218:219], v[220:221]
	ds_write_b128 v119, v[216:219] offset:50688
	v_pk_add_f32 v[216:217], v[124:125], v[158:159] neg_lo:[0,1] neg_hi:[0,1]
	v_and_b32_e32 v157, 0xffff0000, v157
	v_pk_fma_f32 v[216:217], v[8:9], v[216:217], v[158:159]
	v_pk_add_f32 v[218:219], v[126:127], v[158:159] neg_lo:[0,1] neg_hi:[0,1]
	v_pk_add_f32 v[220:221], v[130:131], v[128:129] neg_lo:[0,1] neg_hi:[0,1]
	v_pk_fma_f32 v[216:217], v[0:1], v[218:219], v[216:217]
	v_pk_add_f32 v[218:219], v[156:157], v[128:129] neg_lo:[0,1] neg_hi:[0,1]
	v_lshlrev_b32_e32 v144, 16, v162
	v_pk_fma_f32 v[218:219], v[10:11], v[218:219], v[128:129]
	v_and_b32_e32 v145, 0xffff0000, v162
	v_pk_fma_f32 v[218:219], v[2:3], v[220:221], v[218:219]
	v_lshlrev_b32_e32 v146, 16, v226
	v_and_b32_e32 v147, 0xffff0000, v226
	ds_write_b128 v119, v[216:219] offset:50944
	v_pk_add_f32 v[216:217], v[144:145], v[142:143] neg_lo:[0,1] neg_hi:[0,1]
	v_lshlrev_b32_e32 v162, 16, v163
	v_and_b32_e32 v163, 0xffff0000, v163
	v_pk_fma_f32 v[216:217], v[4:5], v[216:217], v[142:143]
	v_pk_add_f32 v[218:219], v[146:147], v[142:143] neg_lo:[0,1] neg_hi:[0,1]
	v_lshlrev_b32_e32 v226, 16, v227
	v_and_b32_e32 v227, 0xffff0000, v227
	v_pk_fma_f32 v[216:217], v[16:17], v[218:219], v[216:217]
	v_pk_add_f32 v[218:219], v[162:163], v[148:149] neg_lo:[0,1] neg_hi:[0,1]
	v_pk_add_f32 v[220:221], v[226:227], v[148:149] neg_lo:[0,1] neg_hi:[0,1]
	v_pk_fma_f32 v[218:219], v[6:7], v[218:219], v[148:149]
	s_cmpk_lg_i32 s28, 0x87
	v_pk_fma_f32 v[218:219], v[18:19], v[220:221], v[218:219]
	s_cselect_b64 s[48:49], -1, 0
	s_cmpk_eq_i32 s28, 0x87
	ds_write_b128 v119, v[216:219] offset:51200
	s_waitcnt lgkmcnt(0)
	s_barrier

; template <bool DUAL>
; __device__ __forceinline__ void rwkv_tile(const Params& p, int l, int tile, unsigned char* smem) {
;     ...
;       const int i = (tid >> 4) + 16 * k;
;       const int ri = (d == 0) ? i + 1 : 32 - i;
;       const bf16_t* r0 = raw + ri * 192 + lc;
;       const bf16_t* q0 = pre + (ri - 1) * 192 + lc;
;       float rs[4], ksv[4], vs[4];
; #pragma unroll
;       for (int sl = 0; sl < 3; ++sl) {
;         const uint2 uc = *(const uint2*)(r0 + sl * 64), up = *(const uint2*)(r0 + sl * 64 - 192), un = *(const uint2*)(r0 + sl * 64 + 192);
.LBB0_1468:
	ds_read2_b64 v[64:67], v104 offset1:16
	ds_read_b64 v[76:77], v105
	ds_read2_b64 v[68:71], v104 offset0:32 offset1:48
	ds_read_b64 v[80:81], v106
	ds_read_b64 v[82:83], v107
	ds_read_b64 v[118:119], v108 offset:12928
	ds_read2_b64 v[72:75], v104 offset0:64 offset1:80
	ds_read2_b64 v[216:219], v109 offset1:16
	ds_read_b64 v[152:153], v110
	ds_read2_b64 v[220:223], v109 offset0:32 offset1:48
	ds_read_b64 v[156:157], v111
	ds_read_b64 v[158:159], v112
	ds_read_b64 v[160:161], v113 offset:12928
	ds_read2_b64 v[224:227], v109 offset0:64 offset1:80
	s_add_i32 s56, s28, 1
	v_readlane_b32 s0, v254, 14
	s_cmp_ge_u32 s56, s0
	s_cbranch_scc1 .Lrw_nd_nopf
	s_lshl_b32 s57, s56, 5
	s_sub_i32 s58, 0xe0, s57
	s_and_b64 s[50:51], s[36:37], exec
	s_cselect_b32 s64, s57, s58
	s_sub_i32 s58, 0x11e0, s57
	s_and_b64 s[50:51], s[36:37], exec
	s_cselect_b32 s50, s57, s58
	s_cmp_lt_u32 s28, 7
	s_movk_i32 s0, 0x10ff
	s_cselect_b32 s57, s64, s50
	s_cselect_b32 s58, 0xff, s0
	s_cselect_b32 s59, 0, 0x100
	s_add_i32 s66, s57, -1
	s_cmp_eq_u32 s56, 7
	s_cbranch_scc1 .Lrw_nd_pfslow
	s_cmp_eq_u32 s56, 8
	s_cbranch_scc1 .Lrw_nd_pfslow
	s_cmpk_eq_u32 s56, 0x87
	s_cbranch_scc1 .Lrw_nd_pfslow
	s_and_saveexec_b64 s[50:51], s[42:43]
	v_add_u32_e32 v32, s66, v93
	v_lshlrev_b32_e32 v32, 11, v32
	v_mov_b32_e32 v33, v164
	v_lshl_add_u64 v[32:33], v[84:85], 0, v[32:33]
	global_load_dwordx4 v[32:35], v[32:33], off
	v_add_u32_e32 v28, s66, v94
	v_lshlrev_b32_e32 v28, 11, v28
	v_mov_b32_e32 v29, v164
	v_lshl_add_u64 v[28:29], v[84:85], 0, v[28:29]
	global_load_dwordx4 v[28:31], v[28:29], off
	v_add_u32_e32 v36, s66, v95
	v_lshlrev_b32_e32 v36, 11, v36
	v_mov_b32_e32 v37, v164
	v_lshl_add_u64 v[36:37], v[84:85], 0, v[36:37]
	global_load_dwordx4 v[36:39], v[36:37], off
	v_add_u32_e32 v44, s57, v93
	v_mov_b32_e32 v45, v164
	v_lshlrev_b64 v[44:45], 10, v[44:45]
	v_lshl_add_u64 v[44:45], v[86:87], 0, v[44:45]
	global_load_dwordx4 v[44:47], v[44:45], off
	v_add_u32_e32 v48, s57, v94
	v_mov_b32_e32 v49, v164
	v_lshlrev_b64 v[48:49], 10, v[48:49]
	v_lshl_add_u64 v[48:49], v[86:87], 0, v[48:49]
	global_load_dwordx4 v[48:51], v[48:49], off
	v_add_u32_e32 v52, s57, v95
	v_mov_b32_e32 v53, v164
	v_lshlrev_b64 v[52:53], 10, v[52:53]
	v_lshl_add_u64 v[52:53], v[86:87], 0, v[52:53]
	global_load_dwordx4 v[52:55], v[52:53], off
	s_mov_b64 exec, s[50:51]
	s_andn2_b64 exec, exec, s[46:47]
	v_add_u32_e32 v40, s66, v96
	v_lshlrev_b32_e32 v40, 11, v40
	v_mov_b32_e32 v41, v164
	v_lshl_add_u64 v[40:41], v[84:85], 0, v[40:41]
	global_load_dwordx4 v[40:43], v[40:41], off
	s_mov_b64 exec, s[50:51]
	s_and_b64 exec, exec, s[48:49]
	v_add_u32_e32 v56, s57, v96
	v_mov_b32_e32 v57, v164
	v_lshlrev_b64 v[56:57], 10, v[56:57]
	v_lshl_add_u64 v[56:57], v[86:87], 0, v[56:57]
	global_load_dwordx4 v[56:59], v[56:57], off
	s_mov_b64 exec, s[50:51]
	s_branch .Lrw_nd_nopf

; template <bool DUAL>
; __device__ __forceinline__ void rwkv_tile(const Params& p, int l, int tile, unsigned char* smem) {
;     ...
;       float rs[4], ksv[4], vs[4];
; #pragma unroll
;       for (int sl = 0; sl < 3; ++sl) {
;         const uint2 uc = *(const uint2*)(r0 + sl * 64), up = *(const uint2*)(r0 + sl * 64 - 192), un = *(const uint2*)(r0 + sl * 64 + 192);
;         const float4 m0 = (sl == 0) ? m0r : ((sl == 1) ? m0k : m0v);
;         const float4 m1 = (sl == 0) ? m1r : ((sl == 1) ? m1k : m1v);
;         float* dst = (sl == 0) ? rs : ((sl == 1) ? ksv : vs);
;         float u, a, n;
;         u = __uint_as_float(uc.x << 16); a = __uint_as_float(up.x << 16); n = __uint_as_float(un.x << 16);
;         dst[0] = u + m0.x * (a - u) + m1.x * (n - u);
;         u = __uint_as_float(uc.x & 0xffff0000u); a = __uint_as_float(up.x & 0xffff0000u); n = __uint_as_float(un.x & 0xffff0000u);
;         dst[1] = u + m0.y * (a - u) + m1.y * (n - u);
;         u = __uint_as_float(uc.y << 16); a = __uint_as_float(up.y << 16); n = __uint_as_float(un.y << 16);
;         dst[2] = u + m0.z * (a - u) + m1.z * (n - u);
;         u = __uint_as_float(uc.y & 0xffff0000u); a = __uint_as_float(up.y & 0xffff0000u); n = __uint_as_float(un.y & 0xffff0000u);
;         dst[3] = u + m0.w * (a - u) + m1.w * (n - u);
;       }
;       const uint2 ue = *(const uint2*)(q0), ua = *(const uint2*)(q0 + 64), uk = *(const uint2*)(q0 + 128);
;       const float ew[4] = {__uint_as_float(ue.x << 16), __uint_as_float(ue.x & 0xffff0000u), __uint_as_float(ue.y << 16), __uint_as_float(ue.y & 0xffff0000u)};
;       const float av[4] = {__uint_as_float(ua.x << 16), __uint_as_float(ua.x & 0xffff0000u), __uint_as_float(ua.y << 16), __uint_as_float(ua.y & 0xffff0000u)};
;       const float kk[4] = {__uint_as_float(uk.x << 16), __uint_as_float(uk.x & 0xffff0000u), __uint_as_float(uk.y << 16), __uint_as_float(uk.y & 0xffff0000u)};
;       const float kav[4] = {ka4.x, ka4.y, ka4.z, ka4.w};
;       float4 o0, o1, o2, o3, o4, o5;
;       float* f0 = (float*)&o0; float* f1 = (float*)&o1; float* f2 = (float*)&o2; float* f3 = (float*)&o3; float* f4 = (float*)&o4; float* f5 = (float*)&o5;
; #pragma unroll
;       for (int e = 0; e < 4; ++e) {
;         f0[e] = __expf(-ew[e]);
;         f1[e] = kk[e];
;         f2[e] = kk[e] * av[e];
;         f3[e] = ksv[e] * (1.f + (av[e] - 1.f) * kav[e]);
;         f4[e] = rs[e];
.Lrw_nd_nopf:
	s_waitcnt lgkmcnt(13)
	v_lshlrev_b32_e32 v78, 16, v64
	v_and_b32_e32 v79, 0xffff0000, v64
	v_add_u32_e32 v64, 0x3000, v108
	v_lshlrev_b32_e32 v124, 16, v65
	v_and_b32_e32 v125, 0xffff0000, v65
	v_lshlrev_b32_e32 v128, 16, v66
	v_and_b32_e32 v129, 0xffff0000, v66
	v_lshlrev_b32_e32 v134, 16, v67
	v_and_b32_e32 v135, 0xffff0000, v67
	ds_read2_b64 v[64:67], v64 offset0:48 offset1:64
	s_waitcnt lgkmcnt(12)
	v_lshlrev_b32_e32 v138, 16, v68
	v_and_b32_e32 v139, 0xffff0000, v68
	s_waitcnt lgkmcnt(8)
	v_lshlrev_b32_e32 v132, 16, v72
	v_and_b32_e32 v133, 0xffff0000, v72
	s_waitcnt lgkmcnt(0)
	v_lshlrev_b32_e32 v68, 16, v64
	v_and_b32_e32 v64, 0xffff0000, v64
	v_lshlrev_b32_e32 v72, 16, v65
	v_mul_f32_e32 v64, 0xbfb8aa3b, v64
	v_lshlrev_b32_e32 v126, 16, v71
	v_and_b32_e32 v127, 0xffff0000, v71
	v_and_b32_e32 v65, 0xffff0000, v65
	v_exp_f32_e32 v71, v64
	v_mul_f32_e32 v64, 0xbfb8aa3b, v72
	v_mul_f32_e32 v68, 0xbfb8aa3b, v68
	v_exp_f32_e32 v72, v64
	v_mul_f32_e32 v64, 0xbfb8aa3b, v65
	v_lshlrev_b32_e32 v122, 16, v70
	v_and_b32_e32 v123, 0xffff0000, v70
	v_lshlrev_b32_e32 v136, 16, v73
	v_and_b32_e32 v137, 0xffff0000, v73
	v_exp_f32_e32 v70, v68
	v_exp_f32_e32 v73, v64
	v_lshlrev_b32_e32 v117, 16, v66
	v_lshlrev_b32_e32 v146, 16, v119
	v_lshlrev_b32_e32 v149, 16, v67
	ds_write_b128 v115, v[70:73] offset:25344
	v_and_b32_e32 v71, 16, v66
	v_and_b32_e32 v70, 0xffff0000, v118
	v_lshlrev_b32_e32 v72, 16, v118
	v_and_b32_e32 v73, 0xffff0000, v66
	v_pk_mov_b32 v[64:65], v[116:117], v[70:71] op_sel:[1,0]
	v_and_b32_e32 v151, 16, v67
	v_and_b32_e32 v150, 0xffff0000, v119
	v_lshlrev_b32_e32 v130, 16, v80
	v_and_b32_e32 v131, 0xffff0000, v80
	v_lshlrev_b32_e32 v144, 16, v69
	v_and_b32_e32 v145, 0xffff0000, v69
	v_pk_mul_f32 v[64:65], v[72:73], v[64:65]
	v_and_b32_e32 v147, 0xffff0000, v67
	v_pk_mov_b32 v[66:67], v[148:149], v[150:151] op_sel:[1,0]
	v_mov_b32_e32 v68, v72
	v_mov_b32_e32 v69, v70
	v_mov_b32_e32 v70, v146
	v_mov_b32_e32 v71, v150
	v_pk_mul_f32 v[66:67], v[146:147], v[66:67]
	ds_write_b128 v115, v[68:71] offset:25600
	ds_write_b128 v115, v[64:67] offset:25856
	v_pk_add_f32 v[64:65], v[130:131], v[128:129] neg_lo:[0,1] neg_hi:[0,1]
	v_pk_add_f32 v[66:67], v[132:133], v[128:129] neg_lo:[0,1] neg_hi:[0,1]

; template <bool DUAL>
; __device__ __forceinline__ void rwkv_tile(const Params& p, int l, int tile, unsigned char* smem) {
;     ...
;         u = __uint_as_float(uc.x << 16); a = __uint_as_float(up.x << 16); n = __uint_as_float(un.x << 16);
;         dst[0] = u + m0.x * (a - u) + m1.x * (n - u);
;         u = __uint_as_float(uc.x & 0xffff0000u); a = __uint_as_float(up.x & 0xffff0000u); n = __uint_as_float(un.x & 0xffff0000u);
;         dst[1] = u + m0.y * (a - u) + m1.y * (n - u);
;         u = __uint_as_float(uc.y << 16); a = __uint_as_float(up.y << 16); n = __uint_as_float(un.y << 16);
;         dst[2] = u + m0.z * (a - u) + m1.z * (n - u);
;         u = __uint_as_float(uc.y & 0xffff0000u); a = __uint_as_float(up.y & 0xffff0000u); n = __uint_as_float(un.y & 0xffff0000u);
;         dst[3] = u + m0.w * (a - u) + m1.w * (n - u);
	v_pk_fma_f32 v[64:65], v[12:13], v[64:65], v[128:129]
	v_mov_b32_e32 v72, v117

; template <bool DUAL>
; __device__ __forceinline__ void rwkv_tile(const Params& p, int l, int tile, unsigned char* smem) {
;     ...
;         u = __uint_as_float(uc.x << 16); a = __uint_as_float(up.x << 16); n = __uint_as_float(un.x << 16);
;         dst[0] = u + m0.x * (a - u) + m1.x * (n - u);
;         u = __uint_as_float(uc.x & 0xffff0000u); a = __uint_as_float(up.x & 0xffff0000u); n = __uint_as_float(un.x & 0xffff0000u);
;         dst[1] = u + m0.y * (a - u) + m1.y * (n - u);
;         u = __uint_as_float(uc.y << 16); a = __uint_as_float(up.y << 16); n = __uint_as_float(un.y << 16);
;         dst[2] = u + m0.z * (a - u) + m1.z * (n - u);
;         u = __uint_as_float(uc.y & 0xffff0000u); a = __uint_as_float(up.y & 0xffff0000u); n = __uint_as_float(un.y & 0xffff0000u);
;         dst[3] = u + m0.w * (a - u) + m1.w * (n - u);
;       }
;       const uint2 ue = *(const uint2*)(q0), ua = *(const uint2*)(q0 + 64), uk = *(const uint2*)(q0 + 128);
;       const float ew[4] = {__uint_as_float(ue.x << 16), __uint_as_float(ue.x & 0xffff0000u), __uint_as_float(ue.y << 16), __uint_as_float(ue.y & 0xffff0000u)};
;       const float av[4] = {__uint_as_float(ua.x << 16), __uint_as_float(ua.x & 0xffff0000u), __uint_as_float(ua.y << 16), __uint_as_float(ua.y & 0xffff0000u)};
;       const float kk[4] = {__uint_as_float(uk.x << 16), __uint_as_float(uk.x & 0xffff0000u), __uint_as_float(uk.y << 16), __uint_as_float(uk.y & 0xffff0000u)};
;       const float kav[4] = {ka4.x, ka4.y, ka4.z, ka4.w};
;       float4 o0, o1, o2, o3, o4, o5;
;       float* f0 = (float*)&o0; float* f1 = (float*)&o1; float* f2 = (float*)&o2; float* f3 = (float*)&o3; float* f4 = (float*)&o4; float* f5 = (float*)&o5;
; #pragma unroll
;       for (int e = 0; e < 4; ++e) {
;         f0[e] = __expf(-ew[e]);
;         f1[e] = kk[e];
;         f2[e] = kk[e] * av[e];
;         f3[e] = ksv[e] * (1.f + (av[e] - 1.f) * kav[e]);
	v_pk_fma_f32 v[64:65], v[20:21], v[66:67], v[64:65]
	v_pk_add_f32 v[66:67], v[72:73], -1.0 op_sel_hi:[1,0]
	v_lshlrev_b32_e32 v80, 16, v81
	v_and_b32_e32 v81, 0xffff0000, v81

; template <bool DUAL>
; __device__ __forceinline__ void rwkv_tile(const Params& p, int l, int tile, unsigned char* smem) {
;     ...
;       const int i = (tid >> 4) + 16 * k;
;       const int ri = (d == 0) ? i + 1 : 32 - i;
;       const bf16_t* r0 = raw + ri * 192 + lc;
;       const bf16_t* q0 = pre + (ri - 1) * 192 + lc;
;       float rs[4], ksv[4], vs[4];
; #pragma unroll
;       for (int sl = 0; sl < 3; ++sl) {
;         const uint2 uc = *(const uint2*)(r0 + sl * 64), up = *(const uint2*)(r0 + sl * 64 - 192), un = *(const uint2*)(r0 + sl * 64 + 192);
;         const float4 m0 = (sl == 0) ? m0r : ((sl == 1) ? m0k : m0v);
;         const float4 m1 = (sl == 0) ? m1r : ((sl == 1) ? m1k : m1v);
;         float* dst = (sl == 0) ? rs : ((sl == 1) ? ksv : vs);
;         float u, a, n;
;         u = __uint_as_float(uc.x << 16); a = __uint_as_float(up.x << 16); n = __uint_as_float(un.x << 16);
;         dst[0] = u + m0.x * (a - u) + m1.x * (n - u);
;         u = __uint_as_float(uc.x & 0xffff0000u); a = __uint_as_float(up.x & 0xffff0000u); n = __uint_as_float(un.x & 0xffff0000u);
;         dst[1] = u + m0.y * (a - u) + m1.y * (n - u);
;         u = __uint_as_float(uc.y << 16); a = __uint_as_float(up.y << 16); n = __uint_as_float(un.y << 16);
;         dst[2] = u + m0.z * (a - u) + m1.z * (n - u);
;         u = __uint_as_float(uc.y & 0xffff0000u); a = __uint_as_float(up.y & 0xffff0000u); n = __uint_as_float(un.y & 0xffff0000u);
;         dst[3] = u + m0.w * (a - u) + m1.w * (n - u);
;       }
;       const uint2 ue = *(const uint2*)(q0), ua = *(const uint2*)(q0 + 64), uk = *(const uint2*)(q0 + 128);
;       const float ew[4] = {__uint_as_float(ue.x << 16), __uint_as_float(ue.x & 0xffff0000u), __uint_as_float(ue.y << 16), __uint_as_float(ue.y & 0xffff0000u)};
;       const float av[4] = {__uint_as_float(ua.x << 16), __uint_as_float(ua.x & 0xffff0000u), __uint_as_float(ua.y << 16), __uint_as_float(ua.y & 0xffff0000u)};
;       const float kk[4] = {__uint_as_float(uk.x << 16), __uint_as_float(uk.x & 0xffff0000u), __uint_as_float(uk.y << 16), __uint_as_float(uk.y & 0xffff0000u)};
;       const float kav[4] = {ka4.x, ka4.y, ka4.z, ka4.w};
;       float4 o0, o1, o2, o3, o4, o5;
;       float* f0 = (float*)&o0; float* f1 = (float*)&o1; float* f2 = (float*)&o2; float* f3 = (float*)&o3; float* f4 = (float*)&o4; float* f5 = (float*)&o5;
; #pragma unroll
	v_pk_fma_f32 v[66:67], v[24:25], v[66:67], 1.0 op_sel_hi:[1,1,0]
	v_pk_add_f32 v[68:69], v[136:137], v[134:135] neg_lo:[0,1] neg_hi:[0,1]
	v_pk_mul_f32 v[64:65], v[64:65], v[66:67]
	v_pk_add_f32 v[66:67], v[80:81], v[134:135] neg_lo:[0,1] neg_hi:[0,1]
	v_mov_b32_e32 v146, v149
	v_pk_fma_f32 v[66:67], v[14:15], v[66:67], v[134:135]
	v_lshlrev_b32_e32 v120, 16, v76
	v_pk_fma_f32 v[66:67], v[22:23], v[68:69], v[66:67]
	v_pk_add_f32 v[68:69], v[146:147], -1.0 op_sel_hi:[1,0]
	v_and_b32_e32 v121, 0xffff0000, v76
	v_pk_fma_f32 v[68:69], v[26:27], v[68:69], 1.0 op_sel_hi:[1,1,0]
	v_lshlrev_b32_e32 v76, 16, v77
	v_pk_mul_f32 v[66:67], v[66:67], v[68:69]
	ds_write_b128 v115, v[64:67] offset:26112
	v_pk_add_f32 v[64:65], v[120:121], v[78:79] neg_lo:[0,1] neg_hi:[0,1]
	v_and_b32_e32 v77, 0xffff0000, v77
	v_pk_fma_f32 v[64:65], v[8:9], v[64:65], v[78:79]
	v_pk_add_f32 v[66:67], v[122:123], v[78:79] neg_lo:[0,1] neg_hi:[0,1]
	v_pk_add_f32 v[68:69], v[126:127], v[124:125] neg_lo:[0,1] neg_hi:[0,1]
	v_pk_fma_f32 v[64:65], v[0:1], v[66:67], v[64:65]
	v_pk_add_f32 v[66:67], v[76:77], v[124:125] neg_lo:[0,1] neg_hi:[0,1]
	v_lshlrev_b32_e32 v140, 16, v82
	v_pk_fma_f32 v[66:67], v[10:11], v[66:67], v[124:125]
	v_and_b32_e32 v141, 0xffff0000, v82
	v_pk_fma_f32 v[66:67], v[2:3], v[68:69], v[66:67]
	v_lshlrev_b32_e32 v142, 16, v74
	v_and_b32_e32 v143, 0xffff0000, v74
	ds_write_b128 v115, v[64:67] offset:26368
	v_pk_add_f32 v[64:65], v[140:141], v[138:139] neg_lo:[0,1] neg_hi:[0,1]
	v_lshlrev_b32_e32 v82, 16, v83
	v_and_b32_e32 v83, 0xffff0000, v83
	v_pk_fma_f32 v[64:65], v[4:5], v[64:65], v[138:139]
	v_pk_add_f32 v[66:67], v[142:143], v[138:139] neg_lo:[0,1] neg_hi:[0,1]
	v_lshlrev_b32_e32 v74, 16, v75
	v_and_b32_e32 v75, 0xffff0000, v75
	v_pk_fma_f32 v[64:65], v[16:17], v[66:67], v[64:65]
	v_pk_add_f32 v[66:67], v[82:83], v[144:145] neg_lo:[0,1] neg_hi:[0,1]
	v_pk_add_f32 v[68:69], v[74:75], v[144:145] neg_lo:[0,1] neg_hi:[0,1]
	v_pk_fma_f32 v[66:67], v[6:7], v[66:67], v[144:145]
	s_add_i32 s56, s28, 1
	v_pk_fma_f32 v[66:67], v[18:19], v[68:69], v[66:67]
	ds_write_b128 v115, v[64:67] offset:26624
	s_waitcnt lgkmcnt(6)
	v_lshlrev_b32_e32 v154, 16, v216
	v_and_b32_e32 v155, 0xffff0000, v216
	v_add_u32_e32 v216, 0x3000, v113
	v_lshlrev_b32_e32 v124, 16, v217
	v_and_b32_e32 v125, 0xffff0000, v217
	v_lshlrev_b32_e32 v128, 16, v218
	v_and_b32_e32 v129, 0xffff0000, v218
	v_lshlrev_b32_e32 v134, 16, v219
	v_and_b32_e32 v135, 0xffff0000, v219
	ds_read2_b64 v[216:219], v216 offset0:48 offset1:64
	s_waitcnt lgkmcnt(5)
	v_lshlrev_b32_e32 v138, 16, v220
	v_and_b32_e32 v139, 0xffff0000, v220
	s_waitcnt lgkmcnt(1)
	v_lshlrev_b32_e32 v132, 16, v224
	v_and_b32_e32 v133, 0xffff0000, v224
	s_waitcnt lgkmcnt(0)
; template <bool DUAL>
; __device__ __forceinline__ void rwkv_tile(const Params& p, int l, int tile, unsigned char* smem) {
;     ...
;       const int i = (tid >> 4) + 16 * k;
;       const int ri = (d == 0) ? i + 1 : 32 - i;
;       const bf16_t* r0 = raw + ri * 192 + lc;
;       const bf16_t* q0 = pre + (ri - 1) * 192 + lc;
;       float rs[4], ksv[4], vs[4];
; #pragma unroll
;       for (int sl = 0; sl < 3; ++sl) {
;         const uint2 uc = *(const uint2*)(r0 + sl * 64), up = *(const uint2*)(r0 + sl * 64 - 192), un = *(const uint2*)(r0 + sl * 64 + 192);
;         const float4 m0 = (sl == 0) ? m0r : ((sl == 1) ? m0k : m0v);
;         const float4 m1 = (sl == 0) ? m1r : ((sl == 1) ? m1k : m1v);
;         float* dst = (sl == 0) ? rs : ((sl == 1) ? ksv : vs);
;         float u, a, n;
;         u = __uint_as_float(uc.x << 16); a = __uint_as_float(up.x << 16); n = __uint_as_float(un.x << 16);
;         dst[0] = u + m0.x * (a - u) + m1.x * (n - u);
;         u = __uint_as_float(uc.x & 0xffff0000u); a = __uint_as_float(up.x & 0xffff0000u); n = __uint_as_float(un.x & 0xffff0000u);
;         dst[1] = u + m0.y * (a - u) + m1.y * (n - u);
;         u = __uint_as_float(uc.y << 16); a = __uint_as_float(up.y << 16); n = __uint_as_float(un.y << 16);
;         dst[2] = u + m0.z * (a - u) + m1.z * (n - u);
;         u = __uint_as_float(uc.y & 0xffff0000u); a = __uint_as_float(up.y & 0xffff0000u); n = __uint_as_float(un.y & 0xffff0000u);
;         dst[3] = u + m0.w * (a - u) + m1.w * (n - u);
;       }
;       const uint2 ue = *(const uint2*)(q0), ua = *(const uint2*)(q0 + 64), uk = *(const uint2*)(q0 + 128);
;       const float ew[4] = {__uint_as_float(ue.x << 16), __uint_as_float(ue.x & 0xffff0000u), __uint_as_float(ue.y << 16), __uint_as_float(ue.y & 0xffff0000u)};
;       const float av[4] = {__uint_as_float(ua.x << 16), __uint_as_float(ua.x & 0xffff0000u), __uint_as_float(ua.y << 16), __uint_as_float(ua.y & 0xffff0000u)};
;       const float kk[4] = {__uint_as_float(uk.x << 16), __uint_as_float(uk.x & 0xffff0000u), __uint_as_float(uk.y << 16), __uint_as_float(uk.y & 0xffff0000u)};
;       const float kav[4] = {ka4.x, ka4.y, ka4.z, ka4.w};
;       float4 o0, o1, o2, o3, o4, o5;
;       float* f0 = (float*)&o0; float* f1 = (float*)&o1; float* f2 = (float*)&o2; float* f3 = (float*)&o3; float* f4 = (float*)&o4; float* f5 = (float*)&o5;
; #pragma unroll
	v_lshlrev_b32_e32 v220, 16, v216
	v_and_b32_e32 v216, 0xffff0000, v216
	v_lshlrev_b32_e32 v224, 16, v217
	v_mul_f32_e32 v216, 0xbfb8aa3b, v216
	v_lshlrev_b32_e32 v126, 16, v223
	v_and_b32_e32 v127, 0xffff0000, v223
	v_and_b32_e32 v217, 0xffff0000, v217
	v_exp_f32_e32 v223, v216
	v_mul_f32_e32 v216, 0xbfb8aa3b, v224
	v_mul_f32_e32 v220, 0xbfb8aa3b, v220
	v_exp_f32_e32 v224, v216
	v_mul_f32_e32 v216, 0xbfb8aa3b, v217
	v_lshlrev_b32_e32 v122, 16, v222
	v_and_b32_e32 v123, 0xffff0000, v222
	v_lshlrev_b32_e32 v136, 16, v225
	v_and_b32_e32 v137, 0xffff0000, v225
	v_exp_f32_e32 v222, v220
	v_exp_f32_e32 v225, v216
	v_lshlrev_b32_e32 v117, 16, v218
	v_lshlrev_b32_e32 v146, 16, v161
	v_lshlrev_b32_e32 v149, 16, v219
	ds_write_b128 v115, v[222:225] offset:49920
	v_and_b32_e32 v223, 16, v218
	v_and_b32_e32 v222, 0xffff0000, v160
	v_lshlrev_b32_e32 v224, 16, v160
	v_and_b32_e32 v225, 0xffff0000, v218
	v_pk_mov_b32 v[216:217], v[116:117], v[222:223] op_sel:[1,0]
	v_and_b32_e32 v151, 16, v219
	v_and_b32_e32 v150, 0xffff0000, v161
	v_lshlrev_b32_e32 v130, 16, v156
	v_and_b32_e32 v131, 0xffff0000, v156
	v_lshlrev_b32_e32 v144, 16, v221
	v_and_b32_e32 v145, 0xffff0000, v221
	v_pk_mul_f32 v[216:217], v[224:225], v[216:217]
	v_and_b32_e32 v147, 0xffff0000, v219
	v_pk_mov_b32 v[218:219], v[148:149], v[150:151] op_sel:[1,0]
	v_mov_b32_e32 v220, v224
	v_mov_b32_e32 v221, v222
	v_mov_b32_e32 v222, v146
	v_mov_b32_e32 v223, v150
	v_pk_mul_f32 v[218:219], v[146:147], v[218:219]
	ds_write_b128 v115, v[220:223] offset:50176
	ds_write_b128 v115, v[216:219] offset:50432
	v_pk_add_f32 v[216:217], v[130:131], v[128:129] neg_lo:[0,1] neg_hi:[0,1]
	v_pk_add_f32 v[218:219], v[132:133], v[128:129] neg_lo:[0,1] neg_hi:[0,1]
	v_pk_fma_f32 v[216:217], v[12:13], v[216:217], v[128:129]
	v_mov_b32_e32 v224, v117
	v_pk_fma_f32 v[216:217], v[20:21], v[218:219], v[216:217]
	v_pk_add_f32 v[218:219], v[224:225], -1.0 op_sel_hi:[1,0]
	v_lshlrev_b32_e32 v156, 16, v157
	v_and_b32_e32 v157, 0xffff0000, v157
	v_pk_fma_f32 v[218:219], v[24:25], v[218:219], 1.0 op_sel_hi:[1,1,0]
	v_pk_add_f32 v[220:221], v[136:137], v[134:135] neg_lo:[0,1] neg_hi:[0,1]
	v_pk_mul_f32 v[216:217], v[216:217], v[218:219]
	v_pk_add_f32 v[218:219], v[156:157], v[134:135] neg_lo:[0,1] neg_hi:[0,1]
	v_mov_b32_e32 v146, v149
	v_pk_fma_f32 v[218:219], v[14:15], v[218:219], v[134:135]
	v_lshlrev_b32_e32 v120, 16, v152
	v_pk_fma_f32 v[218:219], v[22:23], v[220:221], v[218:219]
	v_pk_add_f32 v[220:221], v[146:147], -1.0 op_sel_hi:[1,0]
	v_and_b32_e32 v121, 0xffff0000, v152
	v_pk_fma_f32 v[220:221], v[26:27], v[220:221], 1.0 op_sel_hi:[1,1,0]
	v_lshlrev_b32_e32 v152, 16, v153
	v_pk_mul_f32 v[218:219], v[218:219], v[220:221]
	ds_write_b128 v115, v[216:219] offset:50688
	v_pk_add_f32 v[216:217], v[120:121], v[154:155] neg_lo:[0,1] neg_hi:[0,1]
	v_and_b32_e32 v153, 0xffff0000, v153
	v_pk_fma_f32 v[216:217], v[8:9], v[216:217], v[154:155]
	v_pk_add_f32 v[218:219], v[122:123], v[154:155] neg_lo:[0,1] neg_hi:[0,1]
	v_pk_add_f32 v[220:221], v[126:127], v[124:125] neg_lo:[0,1] neg_hi:[0,1]
	v_pk_fma_f32 v[216:217], v[0:1], v[218:219], v[216:217]
	v_pk_add_f32 v[218:219], v[152:153], v[124:125] neg_lo:[0,1] neg_hi:[0,1]
	v_lshlrev_b32_e32 v140, 16, v158
	v_pk_fma_f32 v[218:219], v[10:11], v[218:219], v[124:125]
	v_and_b32_e32 v141, 0xffff0000, v158
	v_pk_fma_f32 v[218:219], v[2:3], v[220:221], v[218:219]
	v_lshlrev_b32_e32 v142, 16, v226
	v_and_b32_e32 v143, 0xffff0000, v226
	ds_write_b128 v115, v[216:219] offset:50944
	v_pk_add_f32 v[216:217], v[140:141], v[138:139] neg_lo:[0,1] neg_hi:[0,1]
	v_readlane_b32 s0, v254, 14
	v_lshlrev_b32_e32 v158, 16, v159
	v_and_b32_e32 v159, 0xffff0000, v159
	v_pk_fma_f32 v[216:217], v[4:5], v[216:217], v[138:139]
	v_pk_add_f32 v[218:219], v[142:143], v[138:139] neg_lo:[0,1] neg_hi:[0,1]
	s_cmp_lt_u32 s56, s0
	v_lshlrev_b32_e32 v226, 16, v227
	v_and_b32_e32 v227, 0xffff0000, v227
	v_pk_fma_f32 v[216:217], v[16:17], v[218:219], v[216:217]
	v_pk_add_f32 v[218:219], v[158:159], v[144:145] neg_lo:[0,1] neg_hi:[0,1]
	s_cselect_b64 s[54:55], -1, 0
	s_cmp_ge_u32 s56, s0
	v_pk_fma_f32 v[218:219], v[6:7], v[218:219], v[144:145]
	v_pk_add_f32 v[220:221], v[226:227], v[144:145] neg_lo:[0,1] neg_hi:[0,1]
	s_cselect_b64 s[52:53], -1, 0
	v_pk_fma_f32 v[218:219], v[18:19], v[220:221], v[218:219]
	s_and_b64 vcc, exec, s[52:53]
	ds_write_b128 v115, v[216:219] offset:51200
	s_waitcnt lgkmcnt(0)
	s_barrier
